# half of the workgroups run their 64x64 sample-row tile before the 256x256 tile in the N=1024 GEMM phases (small tile overlaps the other half's residual epilogue)
# speedup vs baseline: 1.0240x; 1.0033x over previous
; DI unsigned xb_ld(unsigned* p)              { return __hip_atomic_load(p, __ATOMIC_RELAXED, __HIP_MEMORY_SCOPE_AGENT); }
; DI void xcd_barrier_complete(unsigned* bar, unsigned x, unsigned& nloc, unsigned& nx) {
;     ...
;         for (unsigned j = 0; j < 16; ++j) { const unsigned c = xb_ld(&bar[XB_XCNT(j)]); sum += c; cnt += (c > 0u) ? 1u : 0u; mine = (j == x) ? c : mine; }
; __global__ void __launch_bounds__(512, 2) fwd_megakernel(Params p) {
;     ...
;     float* Y = p.out + O_YP;
;     float* SS = (float*)(p.ws + SSO);
;     for (int s = 0; s < 8; ++s) {
;         if (s == 1) {
;             for (int rep = 0; rep < REP_P2A; ++rep)
;             for (int it = bid; it < 1024; it += G) { for (int r2 = 0; r2 < REP_DELTA; ++r2) delta_unit(p, lds, it >> 2, it & 3); }
;             xcd_barrier(xb);
;             for (int rep = 0; rep < REP_SYNC; ++rep) xcd_barrier(xb);
;             for (int rep = 0; rep < REP_SCAN; ++rep) {
;             if (bid < 64) { const int bh = bid >> 3, sl = bid & 7; scan_unit(p, lds, (bh >> 2) * 128, 128, bh >> 2, bh & 3, sl, false); }
;             else { const int nb = (G > 64) ? G - 64 : 1;
;                 for (int bh = (G > 64 ? bid - 64 : bid); bh < 64; bh += nb) {
;                     if (rep == 0) delta_unit(p, lds, 256 + (bh >> 2), bh & 3);
;                     __threadfence(); __syncthreads();
;                     scan_sample(p, lds, bh >> 2, bh & 3);
;                 }
;                 if (rep == 0) { for (int it = (G > 64 ? bid - 64 : bid); it < NCF; it += nb) { for (int r2 = 0; r2 < REP_CONF; ++r2) conf_unit(p, lds, it); }
;                     int t2 = threadIdx.x; asm volatile("" : "+v"(t2)); weight_transposes(p, 0, (G > 64 ? bid - 64 : bid) * 8 + (t2 >> 6), nb * 8, t2 & 63, 768, 3072);
;                     weight_transposes(p, 1, (G > 64 ? bid - 64 : bid) * 8 + (t2 >> 6), nb * 8, t2 & 63, 0, 3072); } }
;             }
.LBB0_100:
	s_or_b64 exec, exec, s[0:1]
	s_cmpk_lt_i32 s33, 0x400
	s_cselect_b64 s[4:5], -1, 0
	v_writelane_b32 v252, s4, 4
	s_mul_i32 s0, s91, s90
	s_mul_i32 s84, s0, s2
	v_writelane_b32 v252, s5, 5
	v_lshl_add_u64 v[0:1], v[0:1], 2, s[22:23]
	v_readlane_b32 s28, v252, 0
	v_readlane_b32 s30, v252, 2
	v_readlane_b32 s31, v252, 3
	s_add_u32 s80, s30, 0x44a7000
	s_addc_u32 s81, s31, 0
	s_add_u32 s73, s30, 0x77a7000
	s_addc_u32 s76, s31, 0
	s_add_u32 s82, s88, 0xfcbb000
	s_addc_u32 s83, s89, 0
	s_add_u32 s0, s88, 0xfcbc300
	s_addc_u32 s1, s89, 0
	s_add_u32 s34, s88, 0xfcbc500
	s_addc_u32 s35, s89, 0
	s_add_u32 s36, s88, 0xfcbc600
	s_addc_u32 s37, s89, 0
	s_add_u32 s38, s88, 0xfcbc700
	v_readlane_b32 s29, v252, 1
	v_writelane_b32 v252, s0, 6
	s_addc_u32 s39, s89, 0
	v_mbcnt_hi_u32_b32 v192, -1, v165
	v_writelane_b32 v252, s1, 7
	s_add_u32 s0, s88, 0xfcbc800
	s_addc_u32 s1, s89, 0
	v_writelane_b32 v252, s0, 8
	v_and_b32_e32 v194, 64, v192
	s_mov_b32 s93, 0
	v_writelane_b32 v252, s1, 9
	s_add_u32 s0, s88, 0xfcbc900
	s_addc_u32 s1, s89, 0
	v_writelane_b32 v252, s0, 10
	s_movk_i32 s94, 0xe000
	v_mov_b32_e32 v181, 0
	v_writelane_b32 v252, s1, 11
	s_add_u32 s0, s88, 0xfcbca00
	s_addc_u32 s1, s89, 0
	v_writelane_b32 v252, s0, 12
	v_mov_b32_e32 v190, 1
	v_mov_b32_e32 v191, 0x358637bd
	v_writelane_b32 v252, s1, 13
	s_add_u32 s0, s88, 0xfcbcb00
	s_addc_u32 s1, s89, 0
	v_writelane_b32 v252, s0, 14
	v_xor_b32_e32 v193, 1, v192
	v_add_u32_e32 v195, 64, v194
	v_writelane_b32 v252, s1, 15
	s_add_u32 s0, s88, 0xfcbcc00
	s_addc_u32 s1, s89, 0
	v_writelane_b32 v252, s0, 16
	v_xor_b32_e32 v196, 2, v192
	v_xor_b32_e32 v197, 4, v192
	v_writelane_b32 v252, s1, 17
	s_mov_b64 s[0:1], 0x1400
	v_lshl_add_u64 v[184:185], v[0:1], 0, s[0:1]
	s_mov_b64 s[0:1], 0x2400
	v_lshl_add_u64 v[186:187], v[0:1], 0, s[0:1]
	s_add_u32 s0, s88, 0xfcbcd00
	s_addc_u32 s1, s89, 0
	v_writelane_b32 v252, s0, 18
	v_mov_b32_e32 v198, 0x41b17218
	v_mov_b32_e32 v199, 0xf149f2ca
	v_writelane_b32 v252, s1, 19
	s_add_u32 s0, s88, 0xfcbce00
	s_addc_u32 s1, s89, 0
	v_writelane_b32 v252, s0, 20
	v_mov_b32_e32 v200, 0xfffffef0
	v_mov_b32_e32 v201, 0xffffbc00
	v_writelane_b32 v252, s1, 21
	s_add_u32 s0, s88, 0xfcbcf00
	s_addc_u32 s1, s89, 0
	v_writelane_b32 v252, s0, 22
	v_not_b32_e32 v203, 63
	v_mov_b32_e32 v204, 0x3c00
	v_writelane_b32 v252, s1, 23
	s_add_u32 s0, s88, 0xfcbd000
	s_addc_u32 s1, s89, 0
	v_writelane_b32 v252, s0, 24
	v_mov_b32_e32 v205, 0x100
	v_mov_b32_e32 v206, 0x140
	v_writelane_b32 v252, s1, 25
	s_add_u32 s0, s88, 0xfcbd100
	s_addc_u32 s1, s89, 0
	v_writelane_b32 v252, s0, 26
	v_mov_b32_e32 v207, 0x180
	v_mov_b32_e32 v208, 0x1c0
	v_writelane_b32 v252, s1, 27
	s_add_u32 s0, s88, 0xfcbd200
	s_addc_u32 s1, s89, 0
	v_writelane_b32 v252, s0, 28
	v_mov_b32_e32 v209, 0x400
	v_mov_b32_e32 v210, 0x800
	v_writelane_b32 v252, s1, 29
	s_add_u32 s0, s88, 0xfcbd300
	s_addc_u32 s1, s89, 0
	v_writelane_b32 v252, s0, 30
	v_mov_b32_e32 v211, 0xc00
	s_movk_i32 s91, 0x1800
	v_writelane_b32 v252, s1, 31
	s_add_u32 s0, s88, 0xfcbd400
	s_addc_u32 s1, s89, 0
	v_writelane_b32 v252, s0, 32
	s_cmp_eq_u32 s3, 15
	s_movk_i32 s77, 0x810
	v_writelane_b32 v252, s1, 33
	s_cselect_b64 s[0:1], -1, 0
	v_writelane_b32 v252, s0, 34
	s_cmp_eq_u32 s3, 14
	s_mov_b32 s70, 0x3db504f3
	v_writelane_b32 v252, s1, 35
	s_cselect_b64 s[0:1], -1, 0
	v_writelane_b32 v252, s0, 36
	s_cmp_eq_u32 s3, 13
	s_mov_b32 s71, 0xbfb8aa3b
	v_writelane_b32 v252, s1, 37
	s_cselect_b64 s[0:1], -1, 0
	v_writelane_b32 v252, s0, 38
	s_cmp_eq_u32 s3, 12
	s_mov_b32 s95, -1
	v_writelane_b32 v252, s1, 39
	s_cselect_b64 s[0:1], -1, 0
	v_writelane_b32 v252, s0, 40
	s_cmp_eq_u32 s3, 11
	s_mov_b32 s86, s93
	v_writelane_b32 v252, s1, 41
	s_cselect_b64 s[0:1], -1, 0
	v_writelane_b32 v252, s0, 42
	s_cmp_eq_u32 s3, 10
	s_nop 0
	v_writelane_b32 v252, s1, 43
	s_cselect_b64 s[0:1], -1, 0
	v_writelane_b32 v252, s0, 44
	s_cmp_eq_u32 s3, 9
	s_barrier
	v_writelane_b32 v252, s1, 45
	s_cselect_b64 s[0:1], -1, 0
	v_writelane_b32 v252, s0, 46
	s_cmp_eq_u32 s3, 8
	s_nop 0
	v_writelane_b32 v252, s1, 47
	s_cselect_b64 s[0:1], -1, 0
	v_writelane_b32 v252, s0, 48
	s_cmp_eq_u32 s3, 7
	s_nop 0
	v_writelane_b32 v252, s1, 49
	s_cselect_b64 s[0:1], -1, 0
	v_writelane_b32 v252, s0, 50
	s_cmp_eq_u32 s3, 6
	s_nop 0
	v_writelane_b32 v252, s1, 51
	s_cselect_b64 s[0:1], -1, 0
	v_writelane_b32 v252, s0, 52
	s_cmp_eq_u32 s3, 5
	s_nop 0
	v_writelane_b32 v252, s1, 53
	s_cselect_b64 s[0:1], -1, 0
	v_writelane_b32 v252, s0, 54
	s_cmp_eq_u32 s3, 4
	s_nop 0
	v_writelane_b32 v252, s1, 55
	s_cselect_b64 s[0:1], -1, 0
	v_writelane_b32 v252, s0, 56
	s_cmp_eq_u32 s3, 3
	s_nop 0
	v_writelane_b32 v252, s1, 57
	s_cselect_b64 s[0:1], -1, 0
	v_writelane_b32 v252, s0, 58
	s_cmp_eq_u32 s3, 2
	s_nop 0
	v_writelane_b32 v252, s1, 59
	s_cselect_b64 s[0:1], -1, 0
	v_writelane_b32 v252, s0, 60
	s_cmp_eq_u32 s3, 1
	s_nop 0
	v_writelane_b32 v252, s1, 61
	s_cselect_b64 s[0:1], -1, 0
	v_writelane_b32 v252, s0, 62
	s_cmp_eq_u32 s3, 0
	s_nop 0
	v_writelane_b32 v252, s1, 63
	s_cselect_b64 s[0:1], -1, 0
	v_writelane_b32 v254, s0, 0
	s_nop 1
	v_writelane_b32 v254, s1, 1
	s_add_u32 s0, s88, 0xfcbf500
	s_addc_u32 s1, s89, 0
	v_writelane_b32 v254, s0, 2
	s_nop 1
	v_writelane_b32 v254, s1, 3
	s_add_u32 s0, s88, 0xfcbf600
	s_addc_u32 s1, s89, 0
	v_writelane_b32 v254, s0, 4
	s_cmp_gt_i32 s33, 63
	s_nop 0
	v_writelane_b32 v254, s1, 5
	s_cselect_b64 s[0:1], -1, 0
	v_writelane_b32 v254, s0, 6
	s_max_i32 s3, s90, 0x41
	s_nop 0
	v_writelane_b32 v254, s1, 7
	s_sub_i32 s1, s3, 64
	s_sub_i32 s0, s33, 64
	s_cmp_gt_i32 s90, 64
	s_cselect_b32 s24, s0, s33
	s_cmp_lt_i32 s24, 64
	s_cselect_b64 s[4:5], -1, 0
	v_writelane_b32 v254, s4, 8
; __global__ void __launch_bounds__(512, 2) fwd_megakernel(Params p) {
;     ...
;             if (bid < 64) { const int bh = bid >> 3, sl = bid & 7; scan_unit(p, lds, (bh >> 2) * 128, 128, bh >> 2, bh & 3, sl, false); }
;             else { const int nb = (G > 64) ? G - 64 : 1;
;                 for (int bh = (G > 64 ? bid - 64 : bid); bh < 64; bh += nb) {
;                     if (rep == 0) delta_unit(p, lds, 256 + (bh >> 2), bh & 3);
;                     __threadfence(); __syncthreads();
;                     scan_sample(p, lds, bh >> 2, bh & 3);
;                 }
;                 if (rep == 0) { for (int it = (G > 64 ? bid - 64 : bid); it < NCF; it += nb) { for (int r2 = 0; r2 < REP_CONF; ++r2) conf_unit(p, lds, it); }
;                     int t2 = threadIdx.x; asm volatile("" : "+v"(t2)); weight_transposes(p, 0, (G > 64 ? bid - 64 : bid) * 8 + (t2 >> 6), nb * 8, t2 & 63, 768, 3072);
;                     weight_transposes(p, 1, (G > 64 ? bid - 64 : bid) * 8 + (t2 >> 6), nb * 8, t2 & 63, 0, 3072); } }
	s_add_u32 s0, s30, 0xc4a7000
	s_nop 0
	v_writelane_b32 v254, s5, 9
	v_writelane_b32 v254, s0, 10
	s_addc_u32 s0, s31, 0
	s_cmpk_lt_i32 s24, 0x220
	v_writelane_b32 v254, s0, 11
	s_cselect_b64 s[4:5], -1, 0
	v_writelane_b32 v254, s4, 12
	s_nop 1
	v_writelane_b32 v254, s5, 13
	s_add_u32 s4, s88, 0x8500000
	s_addc_u32 s5, s89, 0
	v_writelane_b32 v254, s4, 14
	s_lshl_b32 s0, s24, 3
	s_nop 0
	v_writelane_b32 v254, s5, 15
	v_writelane_b32 v254, s0, 16
	v_writelane_b32 v254, s1, 17
	s_lshl_b32 s0, s1, 3
	v_writelane_b32 v254, s0, 18
	s_add_u32 s0, s88, 0x2000000
	s_addc_u32 s1, s89, 0
	v_writelane_b32 v254, s0, 19
	s_nop 1
	v_writelane_b32 v254, s1, 20
	s_add_u32 s0, s88, 0x1000000
	s_addc_u32 s1, s89, 0
	v_writelane_b32 v254, s0, 21
	s_nop 1
	v_writelane_b32 v254, s1, 22
	s_add_u32 s0, s88, 0x600000
	s_addc_u32 s1, s89, 0
	v_writelane_b32 v254, s0, 23
	s_nop 1
	v_writelane_b32 v254, s1, 24
	s_add_u32 s0, s28, 0x1000000
	s_addc_u32 s1, s29, 0
	v_writelane_b32 v254, s0, 25
	s_nop 1
	v_writelane_b32 v254, s1, 26
	s_add_u32 s0, s88, 0x2800000
	s_addc_u32 s1, s89, 0
	v_writelane_b32 v254, s0, 27
	s_nop 1
	v_writelane_b32 v254, s1, 28
	s_nop 0
	v_readlane_b32 s4, v254, 29
	v_readlane_b32 s18, v254, 43
	v_readlane_b32 s19, v254, 44
	s_add_u32 s0, s18, 0x1000000
	s_addc_u32 s1, s19, 0
	v_readlane_b32 s5, v254, 30
	v_readlane_b32 s6, v254, 31
	v_readlane_b32 s7, v254, 32
	v_readlane_b32 s8, v254, 33
	v_readlane_b32 s9, v254, 34
	v_readlane_b32 s10, v254, 35
	v_readlane_b32 s11, v254, 36
	v_readlane_b32 s12, v254, 37
	v_readlane_b32 s13, v254, 38
	v_readlane_b32 s14, v254, 39
	v_readlane_b32 s15, v254, 40
	v_readlane_b32 s16, v254, 41
	v_readlane_b32 s17, v254, 42
	v_writelane_b32 v254, s0, 45
	s_nop 1
	v_writelane_b32 v254, s1, 46
	s_add_u32 s0, s88, 0x1800000
	s_addc_u32 s1, s89, 0
	v_writelane_b32 v254, s0, 47
	s_nop 1
	v_writelane_b32 v254, s1, 48
	s_add_u32 s0, s88, 0xe00000
	s_addc_u32 s1, s89, 0
	v_writelane_b32 v254, s0, 49
	s_nop 1
	v_writelane_b32 v254, s1, 50
	s_add_u32 s0, s88, 0x800000
	s_addc_u32 s1, s89, 0
	v_writelane_b32 v254, s0, 51
	s_bfe_u32 s4, s33, 0x10002
	s_and_b32 s7, s33, 3
	v_writelane_b32 v254, s1, 52
	s_bfe_u32 s0, s33, 0x30003
	s_lshl_b32 s1, s0, 10
	s_addk_i32 s1, 0x7000
	v_writelane_b32 v254, s1, 53
	s_lshl_b32 s1, s4, 9
	s_or_b32 s1, s7, s1
	s_lshl_b32 s8, s4, 7
	s_mul_i32 s6, s1, 0x12000
	s_mul_hi_i32 s5, s1, 0x12000
	s_add_u32 s10, s73, s6
	s_addc_u32 s11, s76, s5
	s_or_b32 s5, s1, 4
	v_writelane_b32 v254, s10, 54
	s_mul_hi_i32 s6, s5, 0x12000
	s_mul_i32 s5, s5, 0x12000
	v_writelane_b32 v254, s11, 55
	s_add_u32 s10, s73, s5
	s_addc_u32 s11, s76, s6
	s_or_b32 s1, s1, 8
	v_writelane_b32 v254, s10, 56
	s_mul_hi_i32 s5, s1, 0x12000
	s_mul_i32 s1, s1, 0x12000
	v_writelane_b32 v254, s11, 57
	s_add_u32 s10, s73, s1
	s_addc_u32 s11, s76, s5
	v_writelane_b32 v254, s10, 58
	s_or_b32 s1, s8, 4
	s_nop 0
	v_writelane_b32 v254, s11, 59
	v_writelane_b32 v254, s1, 60
	v_writelane_b32 v254, s8, 61
	s_or_b32 s1, s8, 5
	v_writelane_b32 v254, s1, 62
	s_lshl_b32 s1, s0, 4
	v_writelane_b32 v254, s1, 63
	s_lshl_b32 s1, s7, 9
	s_add_u32 s1, s80, s1
	s_addc_u32 s5, s81, 0
	s_lshl_b32 s0, s0, 6
	s_add_u32 s0, s1, s0
	s_addc_u32 s1, s5, 0
	v_writelane_b32 v253, s0, 0
	s_nop 1
	v_writelane_b32 v253, s1, 1
	s_lshl_b32 s0, s4, 2
	s_or_b32 s0, s0, s7
	s_ashr_i32 s1, s0, 31
	s_lshl_b64 s[0:1], s[0:1], 16
	s_add_u32 s0, s30, s0
	s_addc_u32 s1, s31, s1
	s_add_u32 s0, s0, 0x4400000
	v_writelane_b32 v253, s7, 2
	s_addc_u32 s1, s1, 0
	v_writelane_b32 v253, s0, 3
	s_nop 1
	v_writelane_b32 v253, s1, 4
	s_add_u32 s0, s88, 0x7400000
	s_addc_u32 s1, s89, 0
	v_writelane_b32 v253, s0, 5
	s_nop 1
	v_writelane_b32 v253, s1, 6
	s_add_u32 s0, s88, 0xfcbf7b4
	s_addc_u32 s1, s89, 0
	v_writelane_b32 v253, s0, 7
	s_nop 1
	v_writelane_b32 v253, s1, 8
	s_add_u32 s0, s88, 0xfcbf7b0
	s_addc_u32 s1, s89, 0
	v_writelane_b32 v253, s0, 9
	s_nop 1
	v_writelane_b32 v253, s1, 10
	s_add_u32 s0, s88, 0x5200000
	s_addc_u32 s1, s89, 0
; __global__ void __launch_bounds__(512, 2) fwd_megakernel(Params p) {
;     ...
;     for (int s = 0; s < 8; ++s) {
;         if (s == 1) {
;             for (int rep = 0; rep < REP_P2A; ++rep)
;             for (int it = bid; it < 1024; it += G) { for (int r2 = 0; r2 < REP_DELTA; ++r2) delta_unit(p, lds, it >> 2, it & 3); }
;             xcd_barrier(xb);
;             for (int rep = 0; rep < REP_SYNC; ++rep) xcd_barrier(xb);
;             for (int rep = 0; rep < REP_SCAN; ++rep) {
;             if (bid < 64) { const int bh = bid >> 3, sl = bid & 7; scan_unit(p, lds, (bh >> 2) * 128, 128, bh >> 2, bh & 3, sl, false); }
;             else { const int nb = (G > 64) ? G - 64 : 1;
;                 for (int bh = (G > 64 ? bid - 64 : bid); bh < 64; bh += nb) {
;                     if (rep == 0) delta_unit(p, lds, 256 + (bh >> 2), bh & 3);
;                     __threadfence(); __syncthreads();
;                     scan_sample(p, lds, bh >> 2, bh & 3);
;                 }
;                 if (rep == 0) { for (int it = (G > 64 ? bid - 64 : bid); it < NCF; it += nb) { for (int r2 = 0; r2 < REP_CONF; ++r2) conf_unit(p, lds, it); }
;                     int t2 = threadIdx.x; asm volatile("" : "+v"(t2)); weight_transposes(p, 0, (G > 64 ? bid - 64 : bid) * 8 + (t2 >> 6), nb * 8, t2 & 63, 768, 3072);
;                     weight_transposes(p, 1, (G > 64 ? bid - 64 : bid) * 8 + (t2 >> 6), nb * 8, t2 & 63, 0, 3072); } }
;             }
	v_writelane_b32 v253, s0, 11
	s_nop 1
	v_writelane_b32 v253, s1, 12
	s_add_u32 s0, s88, 0xfcaa000
	s_addc_u32 s1, s89, 0
	v_writelane_b32 v253, s0, 13
	s_nop 1
	v_writelane_b32 v253, s1, 14
	s_nop 0
	v_readlane_b32 s8, v253, 15
	v_readlane_b32 s9, v253, 16
	s_add_u32 s0, s8, 0x1000
	s_addc_u32 s1, s9, 0
	v_readlane_b32 s10, v253, 17
	v_readlane_b32 s11, v253, 18
	v_readlane_b32 s12, v253, 19
	v_readlane_b32 s13, v253, 20
	v_readlane_b32 s14, v253, 21
	v_readlane_b32 s15, v253, 22
	v_readlane_b32 s16, v253, 23
	v_readlane_b32 s17, v253, 24
	v_readlane_b32 s18, v253, 25
	v_readlane_b32 s19, v253, 26
	v_readlane_b32 s20, v253, 27
	v_readlane_b32 s21, v253, 28
	v_readlane_b32 s22, v253, 29
	v_readlane_b32 s23, v253, 30
	v_writelane_b32 v253, s0, 31
	s_nop 1
	v_writelane_b32 v253, s1, 32
	s_add_u32 s0, s88, 0xfc99000
	s_addc_u32 s1, s89, 0
	v_writelane_b32 v253, s0, 33
	s_nop 1
	v_writelane_b32 v253, s1, 34
	s_nop 0
	v_readlane_b32 s8, v253, 35
	v_readlane_b32 s22, v253, 49
	v_readlane_b32 s23, v253, 50
	s_add_u32 s0, s22, 0x1000
	s_addc_u32 s1, s23, 0
	v_readlane_b32 s9, v253, 36
	v_readlane_b32 s10, v253, 37
	v_readlane_b32 s11, v253, 38
	v_readlane_b32 s12, v253, 39
	v_readlane_b32 s13, v253, 40
	v_readlane_b32 s14, v253, 41
	v_readlane_b32 s15, v253, 42
	v_readlane_b32 s16, v253, 43
	v_readlane_b32 s17, v253, 44
	v_readlane_b32 s18, v253, 45
	v_readlane_b32 s19, v253, 46
	v_readlane_b32 s20, v253, 47
	v_readlane_b32 s21, v253, 48
	v_writelane_b32 v253, s0, 51
	s_mov_b32 s22, 0x800000
	s_mov_b32 s8, 0x3f317217
	v_writelane_b32 v253, s1, 52
	s_add_u32 s0, s10, 0xfc000000
	s_addc_u32 s1, s11, -1
	v_writelane_b32 v253, s0, 53
	s_mov_b32 s9, 0x7f800000
	s_mov_b32 s10, 0xc2dc0000
	v_writelane_b32 v253, s1, 54
	s_ashr_i32 s0, s33, 31
	v_writelane_b32 v253, s0, 55
	s_lshr_b32 s0, s0, 29
	s_add_i32 s0, s33, s0
	s_ashr_i32 s1, s0, 3
	s_and_b32 s0, s0, -8
	v_writelane_b32 v253, s1, 56
	s_sub_i32 s0, s33, s0
	s_ashr_i32 s1, s90, 31
	s_cmpk_lt_i32 s33, 0x100
	v_writelane_b32 v253, s1, 57
	s_cselect_b64 s[6:7], -1, 0
	v_writelane_b32 v253, s6, 58
	s_add_u32 s1, s30, 0x4480000
	s_movk_i32 s11, 0x110
	v_writelane_b32 v253, s7, 59
	v_writelane_b32 v253, s1, 60
	s_addc_u32 s1, s31, 0
	v_writelane_b32 v253, s1, 61
	v_writelane_b32 v253, s0, 62
	s_lshr_b32 s0, s0, 31
	v_writelane_b32 v253, s0, 63
	s_add_u32 s0, s88, 0xda40000
	v_writelane_b32 v255, s0, 0
	s_addc_u32 s0, s89, 0
	v_writelane_b32 v255, s0, 1
	s_bitcmp1_b32 s24, 0
	v_writelane_b32 v255, s24, 2
	s_cselect_b64 s[0:1], -1, 0
	v_writelane_b32 v255, s0, 3
	s_bitcmp1_b32 s3, 0
	s_movk_i32 s23, 0x90
	v_writelane_b32 v255, s1, 4
	s_cselect_b64 s[0:1], -1, 0
	v_writelane_b32 v255, s0, 5
	s_add_i32 s14, 0, 0x20c00
	s_mov_b32 s6, 0xffffff0
	v_writelane_b32 v255, s1, 6
	s_lshl_b32 s0, s4, 13
	v_writelane_b32 v255, s0, 7
	s_add_i32 s0, 0, 0x25ff8
	v_writelane_b32 v255, s0, 8
	s_add_i32 s0, 0, 0x25ff0
	v_writelane_b32 v255, s0, 9
	s_add_i32 s0, 0, 0x25ff4
	v_writelane_b32 v255, s0, 10
	s_add_i32 s0, 0, 0x232fc
	v_writelane_b32 v255, s0, 11
	s_add_i32 s0, 0, 0x16000
	v_writelane_b32 v255, s0, 12
	s_add_i32 s0, 0, 0x1a400
	v_writelane_b32 v255, s0, 13
	s_add_i32 s0, 0, 0x24800
	v_writelane_b32 v255, s0, 14
	s_add_i32 s0, 0, 0x1d000
	v_writelane_b32 v255, s0, 15
	s_add_i32 s0, 0, 0xf800
	v_writelane_b32 v255, s0, 16
	s_add_i32 s0, 0, 0x1d800
	v_writelane_b32 v255, s0, 17
	v_writelane_b32 v255, s80, 18
	s_add_i32 s7, 0, 0x1c800
	s_mov_b64 s[12:13], 0x80
	v_writelane_b32 v255, s81, 19
	v_writelane_b32 v255, s73, 20
	v_writelane_b32 v255, s76, 21
	v_writelane_b32 v255, s82, 22
	s_nop 1
	v_writelane_b32 v255, s83, 23
	v_writelane_b32 v255, s84, 24
	v_writelane_b32 v255, s96, 25
	s_nop 1
	v_writelane_b32 v255, s97, 26
	v_writelane_b32 v255, s34, 27
	s_nop 1
	v_writelane_b32 v255, s35, 28
	v_writelane_b32 v255, s36, 29
	s_nop 1
	v_writelane_b32 v255, s37, 30
	v_writelane_b32 v255, s38, 31
	s_nop 1
	v_writelane_b32 v255, s39, 32
	s_mov_b32 s101, 0
	s_branch .LBB0_104

; #define LAS __attribute__((address_space(3)))
; __global__ void __launch_bounds__(512, 2) fwd_megakernel(Params p) {
;     ...
;         const bool split_sample = (g.N == 1024);
;         if (split_sample) g.M = TP;
;         pg8::StaticOrder S; S.init(g.M, g.N, G, bid);
;         for (int rep = 0; rep < ((s == 2) ? REP_G2 : 1); ++rep)
;         pg8::gemm_phase<pg8::Epi, pg8::StaticOrder, true, true>((LAS unsigned char*)lds, g, S, E);
;         if (split_sample) { const int ncol = g.N >> 6; for (int u = bid; u < 16 * ncol; u += G) sgemm_unit(lds, g.A, g.Bt, g.K, TP + (u % 16) * 64, (u / 16) * 64, E); }
.LBB0_790:
	s_cmp_lg_u32 s101, 0
	s_cbranch_scc1 .Lg_entry
	s_cmp_eq_u64 s[36:37], 0
	s_cbranch_scc1 .Lg_entry
	s_bitcmp1_b32 s33, 3
	s_cbranch_scc0 .Lg_entry
	s_mov_b32 s101, 1
	s_mov_b32 s98, s5
	s_lshr_b32 s42, s17, 6
	s_branch .LBB0_905

; __global__ void __launch_bounds__(512, 2) fwd_megakernel(Params p) {
;     ...
;         if (split_sample) { const int ncol = g.N >> 6; for (int u = bid; u < 16 * ncol; u += G) sgemm_unit(lds, g.A, g.Bt, g.K, TP + (u % 16) * 64, (u / 16) * 64, E); }
.LBB0_905:
	s_cmp_eq_u32 s101, 2
	s_cbranch_scc0 .Lsg_go
	s_mov_b32 s101, 0
	s_branch .LBB0_938

; #define LAS __attribute__((address_space(3)))
; __global__ void __launch_bounds__(512, 2) fwd_megakernel(Params p) {
;     ...
;         for (int rep = 0; rep < ((s == 2) ? REP_G2 : 1); ++rep)
;         pg8::gemm_phase<pg8::Epi, pg8::StaticOrder, true, true>((LAS unsigned char*)lds, g, S, E);
;         if (split_sample) { const int ncol = g.N >> 6; for (int u = bid; u < 16 * ncol; u += G) sgemm_unit(lds, g.A, g.Bt, g.K, TP + (u % 16) * 64, (u / 16) * 64, E); }
;         if (s < 7) xcd_barrier(xb);
.LBB0_938:
	s_cmp_eq_u32 s101, 1
	s_cbranch_scc0 .Lph_end
	s_mov_b32 s101, 2
	s_mov_b32 s5, s98
	s_mov_b64 s[36:37], -1
	s_branch .LBB0_790
